# grid barrier waiters poll the top-level arrival counter (complete at (g+1)*nx) instead of the generation word bumped one atomic later
# baseline (speedup 1.0000x reference)
.LBB0_691:
	v_readlane_b32 s8, v239, 18
	v_readlane_b32 s9, v239, 19
	s_add_u32 s8, s6, s8
	s_addc_u32 s9, s7, s9
	v_mov_b64_e32 v[4:5], s[8:9]
	flat_atomic_add v3, v[4:5], v185 sc0
	v_cvt_f32_u32_e32 v1, v2
	v_sub_u32_e32 v4, 0, v2
	v_rcp_iflag_f32_e32 v1, v1
	s_nop 0
	v_mul_f32_e32 v1, 0x4f7ffffe, v1
	v_cvt_u32_f32_e32 v1, v1
	v_mul_lo_u32 v4, v4, v1
	v_mul_hi_u32 v4, v1, v4
	v_add_u32_e32 v1, v1, v4
	s_waitcnt vmcnt(0) lgkmcnt(0)
	v_mul_hi_u32 v1, v3, v1
	v_mul_lo_u32 v4, v1, v2
	v_sub_u32_e32 v4, v3, v4
	v_cmp_ge_u32_e32 vcc, v4, v2
	v_add_u32_e32 v5, 1, v1
	s_nop 0
	v_cndmask_b32_e32 v1, v1, v5, vcc
	v_sub_u32_e32 v5, v4, v2
	v_cndmask_b32_e32 v4, v4, v5, vcc
	v_cmp_ge_u32_e32 vcc, v4, v2
	v_add_u32_e32 v4, 1, v1
	s_nop 0
	v_cndmask_b32_e32 v1, v1, v4, vcc
	v_add_u32_e32 v4, 1, v3
	v_mad_u64_u32 v[2:3], s[8:9], v2, v1, v[2:3]
	v_cmp_ne_u32_e32 vcc, v4, v2
	s_and_saveexec_b64 s[8:9], vcc
	s_xor_b64 s[8:9], exec, s[8:9]
	s_cbranch_execz .LBB0_704
	v_add_u32_e32 v4, 1, v1
	v_mul_lo_u32 v4, v4, v0
	s_add_u32 s12, s6, 0x3400
	s_addc_u32 s13, s7, 0
	v_mov_b64_e32 v[2:3], s[12:13]
	flat_load_dword v0, v[2:3] sc1
	s_waitcnt vmcnt(0) lgkmcnt(0)
	v_cmp_lt_u32_e32 vcc, v0, v4
	s_and_saveexec_b64 s[10:11], vcc
	s_cbranch_execz .LBB0_703
	s_mov_b32 s28, 1
	s_mov_b64 s[14:15], 0
	s_branch .LBB0_695

.LBB0_699:
	s_andn2_b64 s[18:19], s[18:19], exec
	s_and_b64 s[24:25], s[24:25], exec
	s_or_b64 s[18:19], s[18:19], s[24:25]
	s_and_saveexec_b64 s[24:25], s[22:23]
	s_cbranch_execz .LBB0_694
	v_mov_b64_e32 v[2:3], s[12:13]
	flat_load_dword v0, v[2:3] sc1
	s_add_i32 s28, s28, 1
	s_or_b64 s[18:19], s[18:19], exec
	s_waitcnt vmcnt(0) lgkmcnt(0)
	v_cmp_ge_u32_e32 vcc, v0, v4
	s_orn2_b64 s[20:21], vcc, exec
	s_branch .LBB0_694

.LBB0_705:
	v_mov_b32_e32 v1, s6
	v_add_co_u32_e32 v2, vcc, 0x3000, v1
	v_mov_b32_e32 v1, s7
	buffer_wbl2 sc1
	s_waitcnt vmcnt(0)
	v_addc_co_u32_e32 v3, vcc, 0, v1, vcc
	flat_atomic_add v1, v[2:3], v185 offset:1024 sc0
	v_cvt_f32_u32_e32 v2, v0
	v_sub_u32_e32 v3, 0, v0
	s_mov_b64 s[12:13], -1
	v_rcp_iflag_f32_e32 v2, v2
	s_nop 0
	v_mul_f32_e32 v2, 0x4f7ffffe, v2
	v_cvt_u32_f32_e32 v2, v2
	v_mul_lo_u32 v3, v3, v2
	v_mul_hi_u32 v3, v2, v3
	v_add_u32_e32 v2, v2, v3
	s_waitcnt vmcnt(0) lgkmcnt(0)
	v_mul_hi_u32 v2, v1, v2
	v_mul_lo_u32 v3, v2, v0
	v_sub_u32_e32 v3, v1, v3
	v_cmp_ge_u32_e32 vcc, v3, v0
	v_add_u32_e32 v4, 1, v2
	s_nop 0
	v_cndmask_b32_e32 v2, v2, v4, vcc
	v_sub_u32_e32 v4, v3, v0
	v_cndmask_b32_e32 v3, v3, v4, vcc
	v_cmp_ge_u32_e32 vcc, v3, v0
	v_add_u32_e32 v3, 1, v2
	s_nop 0
	v_cndmask_b32_e32 v2, v2, v3, vcc
	v_add_u32_e32 v3, 1, v1
	v_mad_u64_u32 v[0:1], s[8:9], v0, v2, v[0:1]
	v_mov_b32_e32 v4, v0
	s_add_u32 s8, s6, 0x3500
	s_addc_u32 s9, s7, 0
	v_cmp_ne_u32_e32 vcc, v3, v0
	v_mov_b64_e32 v[0:1], s[8:9]
	s_and_saveexec_b64 s[10:11], vcc
	s_cbranch_execz .LBB0_717
	s_add_u32 s98, s6, 0x3400
	s_addc_u32 s99, s7, 0
	v_mov_b64_e32 v[0:1], s[98:99]
	flat_load_dword v0, v[0:1] sc1
	s_mov_b64 s[16:17], 0
	s_waitcnt vmcnt(0) lgkmcnt(0)
	v_cmp_lt_u32_e32 vcc, v0, v4
	s_and_saveexec_b64 s[14:15], vcc
	s_cbranch_execz .LBB0_716
	s_add_u32 s12, s6, 0x200
	s_addc_u32 s13, s7, 0
	s_mov_b32 s28, 1
	s_branch .LBB0_709

.LBB0_714:
	v_mov_b64_e32 v[0:1], s[98:99]
	flat_load_dword v0, v[0:1] sc1
	s_add_i32 s28, s28, 1
	s_or_b64 s[22:23], s[22:23], exec
	s_waitcnt vmcnt(0) lgkmcnt(0)
	v_cmp_ge_u32_e32 vcc, v0, v4
	s_orn2_b64 s[20:21], vcc, exec
	s_branch .LBB0_708
